# P10: the first row's norm partial loads are issued at the start of the unit's last K iteration, the second row's wait is deferred to the fifth row group
# speedup vs baseline: 1.0056x; 1.0008x over previous
.LBB0_1360:
	s_cmp_lg_u32 s53, 12
	s_cbranch_scc1 .Lp10_noearly
	v_mov_b32_e32 v250, s26
	v_lshl_add_u32 v250, v250, 8, v1
	v_bfe_u32 v252, v0, 4, 2
	v_lshl_add_u32 v250, v252, 4, v250
	v_mov_b32_e32 v251, 0
	v_lshlrev_b64 v[250:251], 6, v[250:251]
	v_lshl_add_u64 v[250:251], s[12:13], 0, v[250:251]
	global_load_dwordx4 v[230:233], v[250:251], off
	global_load_dwordx4 v[234:237], v[250:251], off offset:16
	global_load_dwordx4 v[238:241], v[250:251], off offset:32
	global_load_dwordx4 v[242:245], v[250:251], off offset:48

.LBB0_1363:
	s_lshl_b32 s1, s26, 8
	v_add_u32_e32 v148, s1, v1
	v_ashrrev_i32_e32 v149, 31, v148
	v_lshlrev_b64 v[146:147], 6, v[148:149]
	v_lshl_add_u64 v[146:147], s[12:13], 0, v[146:147]
	v_mov_b32_e32 v216, 0x2000
	v_mov_b32_e32 v217, 0
	v_lshl_add_u64 v[248:249], v[250:251], 0, v[216:217]
	global_load_dwordx4 v[200:203], v[248:249], off
	global_load_dwordx4 v[204:207], v[248:249], off offset:16
	global_load_dwordx4 v[208:211], v[248:249], off offset:32
	global_load_dwordx4 v[212:215], v[248:249], off offset:48
	s_waitcnt vmcnt(4)
	v_pk_add_f32 v[218:219], v[232:233], v[236:237]
	v_pk_add_f32 v[220:221], v[230:231], v[234:235]
	v_pk_add_f32 v[222:223], v[240:241], v[244:245]
	v_pk_add_f32 v[224:225], v[238:239], v[242:243]
	v_pk_add_f32 v[218:219], v[218:219], v[222:223]
	v_pk_add_f32 v[220:221], v[220:221], v[224:225]
	s_nop 0
	v_pk_mov_b32 v[222:223], v[220:221], v[218:219] op_sel:[1,0]
	v_mov_b32_e32 v221, v219
	v_pk_add_f32 v[220:221], v[222:223], v[220:221]
	s_nop 0
	v_add_f32_e32 v226, v220, v221
	v_mov_b32_e32 v227, v226
	s_nop 1
	v_permlane16_swap_b32_e32 v226, v227
	v_mov_b32_e32 v228, v226
	v_mov_b32_e32 v229, v227
	s_nop 1
	v_permlane32_swap_b32_e32 v226, v228
	v_permlane32_swap_b32_e32 v227, v229
	v_mov_b32_e32 v181, v116
	v_mov_b32_e32 v116, v125
	v_mov_b32_e32 v178, v126
	v_mov_b32_e32 v179, v118
	v_mov_b32_e32 v118, v127
	v_mov_b32_e32 v126, v128
	v_mov_b32_e32 v127, v120
	v_mov_b32_e32 v120, v129
	v_mov_b32_e32 v128, v122
	v_mov_b32_e32 v129, v114
	v_mov_b32_e32 v114, v123
	v_mov_b32_e32 v180, v124
	v_lshl_or_b32 v176, s0, 7, v154
	v_mov_b64_e32 v[146:147], s[10:11]
	v_ashrrev_i32_e32 v177, 31, v176
	v_add_u32_e32 v182, s1, v151
	v_mad_i64_i32 v[124:125], s[2:3], v148, s52, v[146:147]
	v_lshlrev_b64 v[122:123], 1, v[176:177]
	v_ashrrev_i32_e32 v183, 31, v182
	v_lshl_add_u64 v[124:125], v[124:125], 0, v[122:123]
	s_andn2_b64 vcc, exec, s[4:5]
	s_mov_b64 s[4:5], -1
	s_nop 0
	v_lshlrev_b64 v[162:163], 6, v[182:183]
	v_mov_b32_e32 v149, v226
	v_fmamk_f32 v149, v149, 0x3a800000, v158
	v_rsq_f32_e32 v160, v149
	v_lshl_add_u64 v[162:163], s[12:13], 0, v[162:163]
	v_pk_mul_f32 v[116:117], v[116:117], v[160:161] op_sel_hi:[1,0]
	v_pk_mul_f32 v[164:165], v[178:179], v[160:161] op_sel_hi:[1,0]
	v_pk_mul_f32 v[118:119], v[118:119], v[160:161] op_sel_hi:[1,0]
	v_pk_mul_f32 v[126:127], v[126:127], v[160:161] op_sel_hi:[1,0]
	v_pk_mul_f32 v[120:121], v[120:121], v[160:161] op_sel_hi:[1,0]
	v_pk_mul_f32 v[128:129], v[128:129], v[160:161] op_sel_hi:[1,0]
	v_pk_mul_f32 v[114:115], v[114:115], v[160:161] op_sel_hi:[1,0]
	v_pk_mul_f32 v[166:167], v[180:181], v[160:161] op_sel_hi:[1,0]
	v_mul_f32_e32 v171, 0xbfb8aa3b, v117
	v_mul_f32_e32 v149, 0xbfb8aa3b, v165
	v_mul_f32_e32 v159, 0xbfb8aa3b, v119
	v_mul_f32_e32 v160, 0xbfb8aa3b, v127
	v_mul_f32_e32 v161, 0xbfb8aa3b, v121
	v_mul_f32_e32 v168, 0xbfb8aa3b, v129
	v_mul_f32_e32 v169, 0xbfb8aa3b, v115
	v_mul_f32_e32 v170, 0xbfb8aa3b, v167
	v_exp_f32_e32 v171, v171
	v_exp_f32_e32 v149, v149
	v_exp_f32_e32 v159, v159
	v_exp_f32_e32 v160, v160
	v_exp_f32_e32 v161, v161
	v_exp_f32_e32 v168, v168
	v_exp_f32_e32 v169, v169
	v_exp_f32_e32 v170, v170
	v_add_f32_e32 v171, 1.0, v171
	v_add_f32_e32 v149, 1.0, v149
	v_add_f32_e32 v159, 1.0, v159
	v_add_f32_e32 v160, 1.0, v160
	v_add_f32_e32 v161, 1.0, v161
	v_add_f32_e32 v168, 1.0, v168
	v_add_f32_e32 v169, 1.0, v169
	v_add_f32_e32 v170, 1.0, v170
	v_rcp_f32_e32 v171, v171
	v_rcp_f32_e32 v149, v149
	v_rcp_f32_e32 v159, v159
	v_rcp_f32_e32 v160, v160
	v_rcp_f32_e32 v161, v161
	v_rcp_f32_e32 v168, v168
	v_rcp_f32_e32 v169, v169
	v_rcp_f32_e32 v170, v170
	v_mul_f32_e32 v117, v117, v171
	v_mul_f32_e32 v149, v165, v149
	v_mul_f32_e32 v119, v119, v159
	v_mul_f32_e32 v127, v127, v160
	v_mul_f32_e32 v121, v121, v161
	v_mul_f32_e32 v129, v129, v168
	v_mul_f32_e32 v115, v115, v169
	v_mul_f32_e32 v159, v167, v170
	v_mul_f32_e32 v117, v116, v117
	v_mul_f32_e32 v149, v164, v149
	v_mul_f32_e32 v118, v118, v119
	v_mul_f32_e32 v119, v126, v127
	v_mul_f32_e32 v120, v120, v121
	v_mul_f32_e32 v121, v128, v129
	v_mul_f32_e32 v126, v114, v115
	v_mul_f32_e32 v127, v166, v159
	v_cvt_pk_bf16_f32 v114, v149, v118
	v_cvt_pk_bf16_f32 v115, v119, v120
	v_cvt_pk_bf16_f32 v116, v121, v126
	v_cvt_pk_bf16_f32 v117, v127, v117
	global_store_dwordx4 v[124:125], v[114:117], off
	s_nop 0
	s_nop 0
	v_mov_b32_e32 v129, v102
	v_mov_b32_e32 v102, v111
	v_mov_b32_e32 v111, v104
	v_mov_b32_e32 v104, v113
	v_mov_b32_e32 v113, v98
	v_mov_b32_e32 v98, v107
	v_mov_b32_e32 v107, v100
	v_mov_b32_e32 v100, v109
	v_mov_b32_e32 v128, v110
	v_mov_b32_e32 v110, v112
	v_mov_b32_e32 v112, v106
	v_mov_b32_e32 v106, v108
	v_add_u32_e32 v164, s1, v152
	v_mad_i64_i32 v[108:109], s[2:3], v182, s52, v[146:147]
	v_ashrrev_i32_e32 v165, 31, v164
	v_lshl_add_u64 v[108:109], v[108:109], 0, v[122:123]
	s_nop 0
	v_lshlrev_b64 v[116:117], 6, v[164:165]
	v_mov_b32_e32 v114, v227
	v_fmamk_f32 v114, v114, 0x3a800000, v158
	v_rsq_f32_e32 v114, v114
	v_lshl_add_u64 v[116:117], s[12:13], 0, v[116:117]
	v_pk_mul_f32 v[100:101], v[100:101], v[114:115] op_sel_hi:[1,0]
	v_pk_mul_f32 v[118:119], v[128:129], v[114:115] op_sel_hi:[1,0]
	v_pk_mul_f32 v[102:103], v[102:103], v[114:115] op_sel_hi:[1,0]
	v_pk_mul_f32 v[110:111], v[110:111], v[114:115] op_sel_hi:[1,0]
	v_pk_mul_f32 v[104:105], v[104:105], v[114:115] op_sel_hi:[1,0]
	v_pk_mul_f32 v[112:113], v[112:113], v[114:115] op_sel_hi:[1,0]
	v_pk_mul_f32 v[98:99], v[98:99], v[114:115] op_sel_hi:[1,0]
	v_pk_mul_f32 v[106:107], v[106:107], v[114:115] op_sel_hi:[1,0]
	v_mul_f32_e32 v127, 0xbfb8aa3b, v101
	v_mul_f32_e32 v114, 0xbfb8aa3b, v119
	v_mul_f32_e32 v115, 0xbfb8aa3b, v103
	v_mul_f32_e32 v120, 0xbfb8aa3b, v111
	v_mul_f32_e32 v121, 0xbfb8aa3b, v105
	v_mul_f32_e32 v124, 0xbfb8aa3b, v113
	v_mul_f32_e32 v125, 0xbfb8aa3b, v99
	v_mul_f32_e32 v126, 0xbfb8aa3b, v107
	v_exp_f32_e32 v127, v127
	v_exp_f32_e32 v114, v114
	v_exp_f32_e32 v115, v115
	v_exp_f32_e32 v120, v120
	v_exp_f32_e32 v121, v121
	v_exp_f32_e32 v124, v124
	v_exp_f32_e32 v125, v125
	v_exp_f32_e32 v126, v126
	v_add_f32_e32 v127, 1.0, v127
	v_add_f32_e32 v114, 1.0, v114
	v_add_f32_e32 v115, 1.0, v115
	v_add_f32_e32 v120, 1.0, v120
	v_add_f32_e32 v121, 1.0, v121
	v_add_f32_e32 v124, 1.0, v124
	v_add_f32_e32 v125, 1.0, v125
	v_add_f32_e32 v126, 1.0, v126
	v_rcp_f32_e32 v127, v127
	v_rcp_f32_e32 v114, v114
	v_rcp_f32_e32 v115, v115
	v_rcp_f32_e32 v120, v120
	v_rcp_f32_e32 v121, v121
	v_rcp_f32_e32 v124, v124
	v_rcp_f32_e32 v125, v125
	v_rcp_f32_e32 v126, v126
	v_mul_f32_e32 v101, v101, v127
	v_mul_f32_e32 v114, v119, v114
	v_mul_f32_e32 v103, v103, v115
	v_mul_f32_e32 v111, v111, v120
	v_mul_f32_e32 v105, v105, v121
	v_mul_f32_e32 v113, v113, v124
	v_mul_f32_e32 v99, v99, v125
	v_mul_f32_e32 v107, v107, v126
	v_mul_f32_e32 v101, v100, v101
	v_mul_f32_e32 v114, v118, v114
	v_mul_f32_e32 v102, v102, v103
	v_mul_f32_e32 v103, v110, v111
	v_mul_f32_e32 v104, v104, v105
	v_mul_f32_e32 v105, v112, v113
	v_mul_f32_e32 v110, v98, v99
	v_mul_f32_e32 v106, v106, v107
	v_cvt_pk_bf16_f32 v98, v114, v102
	v_cvt_pk_bf16_f32 v99, v103, v104
	v_cvt_pk_bf16_f32 v100, v105, v110
	v_cvt_pk_bf16_f32 v101, v106, v101
	global_store_dwordx4 v[108:109], v[98:101], off
	s_nop 0
	v_mov_b32_e32 v115, v86
	v_mov_b32_e32 v86, v95
	v_mov_b32_e32 v95, v88
	v_mov_b32_e32 v88, v97
	v_mov_b32_e32 v97, v82
	v_mov_b32_e32 v82, v91
	v_mov_b32_e32 v91, v84
	v_mov_b32_e32 v84, v93
	v_mov_b32_e32 v114, v94
	v_mov_b32_e32 v94, v96
	v_mov_b32_e32 v96, v90
	v_mov_b32_e32 v90, v92
	v_add_u32_e32 v116, s1, v153
	v_mad_i64_i32 v[92:93], s[0:1], v164, s52, v[146:147]
	v_ashrrev_i32_e32 v117, 31, v116
	v_lshl_add_u64 v[92:93], v[92:93], 0, v[122:123]
	s_nop 0
	v_lshlrev_b64 v[100:101], 6, v[116:117]
	v_mov_b32_e32 v98, v228
	v_fmamk_f32 v98, v98, 0x3a800000, v158
	v_rsq_f32_e32 v98, v98
	v_lshl_add_u64 v[100:101], s[12:13], 0, v[100:101]
	v_pk_mul_f32 v[84:85], v[84:85], v[98:99] op_sel_hi:[1,0]
	v_pk_mul_f32 v[102:103], v[114:115], v[98:99] op_sel_hi:[1,0]
	v_pk_mul_f32 v[86:87], v[86:87], v[98:99] op_sel_hi:[1,0]
	v_pk_mul_f32 v[94:95], v[94:95], v[98:99] op_sel_hi:[1,0]
	v_pk_mul_f32 v[88:89], v[88:89], v[98:99] op_sel_hi:[1,0]
	v_pk_mul_f32 v[96:97], v[96:97], v[98:99] op_sel_hi:[1,0]
	v_pk_mul_f32 v[82:83], v[82:83], v[98:99] op_sel_hi:[1,0]
	v_pk_mul_f32 v[90:91], v[90:91], v[98:99] op_sel_hi:[1,0]
	v_mul_f32_e32 v109, 0xbfb8aa3b, v85
	v_mul_f32_e32 v98, 0xbfb8aa3b, v103
	v_mul_f32_e32 v99, 0xbfb8aa3b, v87
	v_mul_f32_e32 v104, 0xbfb8aa3b, v95
	v_mul_f32_e32 v105, 0xbfb8aa3b, v89
	v_mul_f32_e32 v106, 0xbfb8aa3b, v97
	v_mul_f32_e32 v107, 0xbfb8aa3b, v83
	v_mul_f32_e32 v108, 0xbfb8aa3b, v91
	v_exp_f32_e32 v109, v109
	v_exp_f32_e32 v98, v98
	v_exp_f32_e32 v99, v99
	v_exp_f32_e32 v104, v104
	v_exp_f32_e32 v105, v105
	v_exp_f32_e32 v106, v106
	v_exp_f32_e32 v107, v107
	v_exp_f32_e32 v108, v108
	v_add_f32_e32 v109, 1.0, v109
	v_add_f32_e32 v98, 1.0, v98
	v_add_f32_e32 v99, 1.0, v99
	v_add_f32_e32 v104, 1.0, v104
	v_add_f32_e32 v105, 1.0, v105
	v_add_f32_e32 v106, 1.0, v106
	v_add_f32_e32 v107, 1.0, v107
	v_add_f32_e32 v108, 1.0, v108
	v_rcp_f32_e32 v109, v109
	v_rcp_f32_e32 v98, v98
	v_rcp_f32_e32 v99, v99
	v_rcp_f32_e32 v104, v104
	v_rcp_f32_e32 v105, v105
	v_rcp_f32_e32 v106, v106
	v_rcp_f32_e32 v107, v107
	v_rcp_f32_e32 v108, v108
	v_mul_f32_e32 v85, v85, v109
	v_mul_f32_e32 v98, v103, v98
	v_mul_f32_e32 v87, v87, v99
	v_mul_f32_e32 v95, v95, v104
	v_mul_f32_e32 v89, v89, v105
	v_mul_f32_e32 v97, v97, v106
	v_mul_f32_e32 v83, v83, v107
	v_mul_f32_e32 v91, v91, v108
	v_mul_f32_e32 v85, v84, v85
	v_mul_f32_e32 v98, v102, v98
	v_mul_f32_e32 v86, v86, v87
	v_mul_f32_e32 v87, v94, v95
	v_mul_f32_e32 v88, v88, v89
	v_mul_f32_e32 v89, v96, v97
	v_mul_f32_e32 v94, v82, v83
	v_mul_f32_e32 v90, v90, v91
	v_cvt_pk_bf16_f32 v82, v98, v86
	v_cvt_pk_bf16_f32 v83, v87, v88
	v_cvt_pk_bf16_f32 v84, v89, v94
	v_cvt_pk_bf16_f32 v85, v90, v85
	global_store_dwordx4 v[92:93], v[82:85], off
	s_nop 0
	v_mov_b32_e32 v99, v70
	v_mov_b32_e32 v70, v79
	v_mov_b32_e32 v79, v72
	v_mov_b32_e32 v72, v81
	v_mov_b32_e32 v81, v66
	v_mov_b32_e32 v66, v75
	v_mov_b32_e32 v75, v68
	v_mov_b32_e32 v68, v77
	v_mov_b32_e32 v98, v78
	v_mov_b32_e32 v78, v80
	v_mov_b32_e32 v80, v74
	v_mov_b32_e32 v74, v76
	v_add_u32_e32 v100, 0x80, v148
	v_mad_i64_i32 v[76:77], s[0:1], v116, s52, v[146:147]
	v_ashrrev_i32_e32 v101, 31, v100
	v_lshl_add_u64 v[76:77], v[76:77], 0, v[122:123]
	s_nop 0
	v_lshlrev_b64 v[84:85], 6, v[100:101]
	v_mov_b32_e32 v82, v229
	v_fmamk_f32 v82, v82, 0x3a800000, v158
	v_rsq_f32_e32 v82, v82
	v_lshl_add_u64 v[84:85], s[12:13], 0, v[84:85]
	v_pk_mul_f32 v[68:69], v[68:69], v[82:83] op_sel_hi:[1,0]
	v_pk_mul_f32 v[86:87], v[98:99], v[82:83] op_sel_hi:[1,0]
	v_pk_mul_f32 v[70:71], v[70:71], v[82:83] op_sel_hi:[1,0]
	v_pk_mul_f32 v[78:79], v[78:79], v[82:83] op_sel_hi:[1,0]
	v_pk_mul_f32 v[72:73], v[72:73], v[82:83] op_sel_hi:[1,0]
	v_pk_mul_f32 v[80:81], v[80:81], v[82:83] op_sel_hi:[1,0]
	v_pk_mul_f32 v[66:67], v[66:67], v[82:83] op_sel_hi:[1,0]
	v_pk_mul_f32 v[74:75], v[74:75], v[82:83] op_sel_hi:[1,0]
	v_mul_f32_e32 v93, 0xbfb8aa3b, v69
	v_mul_f32_e32 v82, 0xbfb8aa3b, v87
	v_mul_f32_e32 v83, 0xbfb8aa3b, v71
	v_mul_f32_e32 v88, 0xbfb8aa3b, v79
	v_mul_f32_e32 v89, 0xbfb8aa3b, v73
	v_mul_f32_e32 v90, 0xbfb8aa3b, v81
	v_mul_f32_e32 v91, 0xbfb8aa3b, v67
	v_mul_f32_e32 v92, 0xbfb8aa3b, v75
	v_exp_f32_e32 v93, v93
	v_exp_f32_e32 v82, v82
	v_exp_f32_e32 v83, v83
	v_exp_f32_e32 v88, v88
	v_exp_f32_e32 v89, v89
	v_exp_f32_e32 v90, v90
	v_exp_f32_e32 v91, v91
	v_exp_f32_e32 v92, v92
	v_add_f32_e32 v93, 1.0, v93
	v_add_f32_e32 v82, 1.0, v82
	v_add_f32_e32 v83, 1.0, v83
	v_add_f32_e32 v88, 1.0, v88
	v_add_f32_e32 v89, 1.0, v89
	v_add_f32_e32 v90, 1.0, v90
	v_add_f32_e32 v91, 1.0, v91
	v_add_f32_e32 v92, 1.0, v92
	v_rcp_f32_e32 v93, v93
	v_rcp_f32_e32 v82, v82
	v_rcp_f32_e32 v83, v83
	v_rcp_f32_e32 v88, v88
	v_rcp_f32_e32 v89, v89
	v_rcp_f32_e32 v90, v90
	v_rcp_f32_e32 v91, v91
	v_rcp_f32_e32 v92, v92
	v_mul_f32_e32 v69, v69, v93
	v_mul_f32_e32 v82, v87, v82
	v_mul_f32_e32 v71, v71, v83
	v_mul_f32_e32 v79, v79, v88
	v_mul_f32_e32 v73, v73, v89
	v_mul_f32_e32 v81, v81, v90
	v_mul_f32_e32 v67, v67, v91
	v_mul_f32_e32 v75, v75, v92
	v_mul_f32_e32 v69, v68, v69
	v_mul_f32_e32 v82, v86, v82
	v_mul_f32_e32 v70, v70, v71
	v_mul_f32_e32 v71, v78, v79
	v_mul_f32_e32 v72, v72, v73
	v_mul_f32_e32 v73, v80, v81
	v_mul_f32_e32 v78, v66, v67
	v_mul_f32_e32 v74, v74, v75
	v_cvt_pk_bf16_f32 v66, v82, v70
	v_cvt_pk_bf16_f32 v67, v71, v72
	v_cvt_pk_bf16_f32 v68, v73, v78
	v_cvt_pk_bf16_f32 v69, v74, v69
	global_store_dwordx4 v[76:77], v[66:69], off
	s_nop 0
	v_mov_b32_e32 v83, v54
	v_mov_b32_e32 v54, v63
	v_mov_b32_e32 v63, v56
	v_mov_b32_e32 v56, v65
	v_mov_b32_e32 v65, v50
	v_mov_b32_e32 v50, v59
	v_mov_b32_e32 v59, v52
	v_mov_b32_e32 v52, v61
	v_mov_b32_e32 v82, v62
	v_mov_b32_e32 v62, v64
	v_mov_b32_e32 v64, v58
	v_mov_b32_e32 v58, v60
	v_add_u32_e32 v84, 0x90, v148
	v_mad_i64_i32 v[60:61], s[0:1], v100, s52, v[146:147]
	v_ashrrev_i32_e32 v85, 31, v84
	v_lshl_add_u64 v[60:61], v[60:61], 0, v[122:123]
	s_nop 0
	v_lshlrev_b64 v[68:69], 6, v[84:85]
	s_waitcnt vmcnt(4)
	v_pk_add_f32 v[218:219], v[202:203], v[206:207]
	v_pk_add_f32 v[220:221], v[200:201], v[204:205]
	v_pk_add_f32 v[222:223], v[210:211], v[214:215]
	v_pk_add_f32 v[224:225], v[208:209], v[212:213]
	v_pk_add_f32 v[218:219], v[218:219], v[222:223]
	v_pk_add_f32 v[220:221], v[220:221], v[224:225]
	s_nop 0
	v_pk_mov_b32 v[222:223], v[220:221], v[218:219] op_sel:[1,0]
	v_mov_b32_e32 v221, v219
	v_pk_add_f32 v[220:221], v[222:223], v[220:221]
	s_nop 0
	v_add_f32_e32 v230, v220, v221
	v_mov_b32_e32 v231, v230
	s_nop 1
	v_permlane16_swap_b32_e32 v230, v231
	v_mov_b32_e32 v232, v230
	v_mov_b32_e32 v233, v231
	s_nop 1
	v_permlane32_swap_b32_e32 v230, v232
	v_permlane32_swap_b32_e32 v231, v233
	v_mov_b32_e32 v66, v230
	v_fmamk_f32 v66, v66, 0x3a800000, v158
	v_rsq_f32_e32 v66, v66
	v_lshl_add_u64 v[68:69], s[12:13], 0, v[68:69]
	v_pk_mul_f32 v[52:53], v[52:53], v[66:67] op_sel_hi:[1,0]
	v_pk_mul_f32 v[70:71], v[82:83], v[66:67] op_sel_hi:[1,0]
	v_pk_mul_f32 v[54:55], v[54:55], v[66:67] op_sel_hi:[1,0]
	v_pk_mul_f32 v[62:63], v[62:63], v[66:67] op_sel_hi:[1,0]
	v_pk_mul_f32 v[56:57], v[56:57], v[66:67] op_sel_hi:[1,0]
	v_pk_mul_f32 v[64:65], v[64:65], v[66:67] op_sel_hi:[1,0]
	v_pk_mul_f32 v[50:51], v[50:51], v[66:67] op_sel_hi:[1,0]
	v_pk_mul_f32 v[58:59], v[58:59], v[66:67] op_sel_hi:[1,0]
	v_mul_f32_e32 v77, 0xbfb8aa3b, v53
	v_mul_f32_e32 v66, 0xbfb8aa3b, v71
	v_mul_f32_e32 v67, 0xbfb8aa3b, v55
	v_mul_f32_e32 v72, 0xbfb8aa3b, v63
	v_mul_f32_e32 v73, 0xbfb8aa3b, v57
	v_mul_f32_e32 v74, 0xbfb8aa3b, v65
	v_mul_f32_e32 v75, 0xbfb8aa3b, v51
	v_mul_f32_e32 v76, 0xbfb8aa3b, v59
	v_exp_f32_e32 v77, v77
	v_exp_f32_e32 v66, v66
	v_exp_f32_e32 v67, v67
	v_exp_f32_e32 v72, v72
	v_exp_f32_e32 v73, v73
	v_exp_f32_e32 v74, v74
	v_exp_f32_e32 v75, v75
	v_exp_f32_e32 v76, v76
	v_add_f32_e32 v77, 1.0, v77
	v_add_f32_e32 v66, 1.0, v66
	v_add_f32_e32 v67, 1.0, v67
	v_add_f32_e32 v72, 1.0, v72
	v_add_f32_e32 v73, 1.0, v73
	v_add_f32_e32 v74, 1.0, v74
	v_add_f32_e32 v75, 1.0, v75
	v_add_f32_e32 v76, 1.0, v76
	v_rcp_f32_e32 v77, v77
	v_rcp_f32_e32 v66, v66
	v_rcp_f32_e32 v67, v67
	v_rcp_f32_e32 v72, v72
	v_rcp_f32_e32 v73, v73
	v_rcp_f32_e32 v74, v74
	v_rcp_f32_e32 v75, v75
	v_rcp_f32_e32 v76, v76
	v_mul_f32_e32 v53, v53, v77
	v_mul_f32_e32 v66, v71, v66
	v_mul_f32_e32 v55, v55, v67
	v_mul_f32_e32 v63, v63, v72
	v_mul_f32_e32 v57, v57, v73
	v_mul_f32_e32 v65, v65, v74
	v_mul_f32_e32 v51, v51, v75
	v_mul_f32_e32 v59, v59, v76
	v_mul_f32_e32 v53, v52, v53
	v_mul_f32_e32 v66, v70, v66
	v_mul_f32_e32 v54, v54, v55
	v_mul_f32_e32 v55, v62, v63
	v_mul_f32_e32 v56, v56, v57
	v_mul_f32_e32 v57, v64, v65
	v_mul_f32_e32 v62, v50, v51
	v_mul_f32_e32 v58, v58, v59
	v_cvt_pk_bf16_f32 v50, v66, v54
	v_cvt_pk_bf16_f32 v51, v55, v56
	v_cvt_pk_bf16_f32 v52, v57, v62
	v_cvt_pk_bf16_f32 v53, v58, v53
	global_store_dwordx4 v[60:61], v[50:53], off
	s_nop 0
	v_mov_b32_e32 v67, v38
	v_mov_b32_e32 v38, v47
	v_mov_b32_e32 v47, v40
	v_mov_b32_e32 v40, v49
	v_mov_b32_e32 v49, v34
	v_mov_b32_e32 v34, v43
	v_mov_b32_e32 v43, v36
	v_mov_b32_e32 v36, v45
	v_mov_b32_e32 v66, v46
	v_mov_b32_e32 v46, v48
	v_mov_b32_e32 v48, v42
	v_mov_b32_e32 v42, v44
	v_add_u32_e32 v68, 0xa0, v148
	v_mad_i64_i32 v[44:45], s[0:1], v84, s52, v[146:147]
	v_ashrrev_i32_e32 v69, 31, v68
	v_lshl_add_u64 v[44:45], v[44:45], 0, v[122:123]
	s_nop 0
	v_lshlrev_b64 v[52:53], 6, v[68:69]
	v_mov_b32_e32 v50, v231
	v_fmamk_f32 v50, v50, 0x3a800000, v158
	v_rsq_f32_e32 v50, v50
	v_lshl_add_u64 v[52:53], s[12:13], 0, v[52:53]
	v_pk_mul_f32 v[36:37], v[36:37], v[50:51] op_sel_hi:[1,0]
	v_pk_mul_f32 v[54:55], v[66:67], v[50:51] op_sel_hi:[1,0]
	v_pk_mul_f32 v[38:39], v[38:39], v[50:51] op_sel_hi:[1,0]
	v_pk_mul_f32 v[46:47], v[46:47], v[50:51] op_sel_hi:[1,0]
	v_pk_mul_f32 v[40:41], v[40:41], v[50:51] op_sel_hi:[1,0]
	v_pk_mul_f32 v[48:49], v[48:49], v[50:51] op_sel_hi:[1,0]
	v_pk_mul_f32 v[34:35], v[34:35], v[50:51] op_sel_hi:[1,0]
	v_pk_mul_f32 v[42:43], v[42:43], v[50:51] op_sel_hi:[1,0]
	v_mul_f32_e32 v61, 0xbfb8aa3b, v37
	v_mul_f32_e32 v50, 0xbfb8aa3b, v55
	v_mul_f32_e32 v51, 0xbfb8aa3b, v39
	v_mul_f32_e32 v56, 0xbfb8aa3b, v47
	v_mul_f32_e32 v57, 0xbfb8aa3b, v41
	v_mul_f32_e32 v58, 0xbfb8aa3b, v49
	v_mul_f32_e32 v59, 0xbfb8aa3b, v35
	v_mul_f32_e32 v60, 0xbfb8aa3b, v43
	v_exp_f32_e32 v61, v61
	v_exp_f32_e32 v50, v50
	v_exp_f32_e32 v51, v51
	v_exp_f32_e32 v56, v56
	v_exp_f32_e32 v57, v57
	v_exp_f32_e32 v58, v58
	v_exp_f32_e32 v59, v59
	v_exp_f32_e32 v60, v60
	v_add_f32_e32 v61, 1.0, v61
	v_add_f32_e32 v50, 1.0, v50
	v_add_f32_e32 v51, 1.0, v51
	v_add_f32_e32 v56, 1.0, v56
	v_add_f32_e32 v57, 1.0, v57
	v_add_f32_e32 v58, 1.0, v58
	v_add_f32_e32 v59, 1.0, v59
	v_add_f32_e32 v60, 1.0, v60
	v_rcp_f32_e32 v61, v61
	v_rcp_f32_e32 v50, v50
	v_rcp_f32_e32 v51, v51
	v_rcp_f32_e32 v56, v56
	v_rcp_f32_e32 v57, v57
	v_rcp_f32_e32 v58, v58
	v_rcp_f32_e32 v59, v59
	v_rcp_f32_e32 v60, v60
	v_mul_f32_e32 v37, v37, v61
	v_mul_f32_e32 v50, v55, v50
	v_mul_f32_e32 v39, v39, v51
	v_mul_f32_e32 v47, v47, v56
	v_mul_f32_e32 v41, v41, v57
	v_mul_f32_e32 v49, v49, v58
	v_mul_f32_e32 v35, v35, v59
	v_mul_f32_e32 v43, v43, v60
	v_mul_f32_e32 v37, v36, v37
	v_mul_f32_e32 v50, v54, v50
	v_mul_f32_e32 v38, v38, v39
	v_mul_f32_e32 v39, v46, v47
	v_mul_f32_e32 v40, v40, v41
	v_mul_f32_e32 v41, v48, v49
	v_mul_f32_e32 v46, v34, v35
	v_mul_f32_e32 v42, v42, v43
	v_cvt_pk_bf16_f32 v34, v50, v38
	v_cvt_pk_bf16_f32 v35, v39, v40
	v_cvt_pk_bf16_f32 v36, v41, v46
	v_cvt_pk_bf16_f32 v37, v42, v37
	global_store_dwordx4 v[44:45], v[34:37], off
	s_nop 0
	v_mov_b32_e32 v51, v22
	v_mov_b32_e32 v22, v31
	v_mov_b32_e32 v31, v24
	v_mov_b32_e32 v24, v33
	v_mov_b32_e32 v33, v18
	v_mov_b32_e32 v18, v27
	v_mov_b32_e32 v27, v20
	v_mov_b32_e32 v20, v29
	v_mov_b32_e32 v50, v30
	v_mov_b32_e32 v30, v32
	v_mov_b32_e32 v32, v26
	v_mov_b32_e32 v26, v28
	v_add_u32_e32 v52, 0xb0, v148
	v_mad_i64_i32 v[28:29], s[0:1], v68, s52, v[146:147]
	v_ashrrev_i32_e32 v53, 31, v52
	v_lshl_add_u64 v[28:29], v[28:29], 0, v[122:123]
	s_nop 0
	v_lshlrev_b64 v[36:37], 6, v[52:53]
	v_mov_b32_e32 v34, v232
	v_fmamk_f32 v34, v34, 0x3a800000, v158
	v_rsq_f32_e32 v34, v34
	v_lshl_add_u64 v[36:37], s[12:13], 0, v[36:37]
	v_pk_mul_f32 v[20:21], v[20:21], v[34:35] op_sel_hi:[1,0]
	v_pk_mul_f32 v[38:39], v[50:51], v[34:35] op_sel_hi:[1,0]
	v_pk_mul_f32 v[22:23], v[22:23], v[34:35] op_sel_hi:[1,0]
	v_pk_mul_f32 v[30:31], v[30:31], v[34:35] op_sel_hi:[1,0]
	v_pk_mul_f32 v[24:25], v[24:25], v[34:35] op_sel_hi:[1,0]
	v_pk_mul_f32 v[32:33], v[32:33], v[34:35] op_sel_hi:[1,0]
	v_pk_mul_f32 v[18:19], v[18:19], v[34:35] op_sel_hi:[1,0]
	v_pk_mul_f32 v[26:27], v[26:27], v[34:35] op_sel_hi:[1,0]
	v_mul_f32_e32 v45, 0xbfb8aa3b, v21
	v_mul_f32_e32 v34, 0xbfb8aa3b, v39
	v_mul_f32_e32 v35, 0xbfb8aa3b, v23
	v_mul_f32_e32 v40, 0xbfb8aa3b, v31
	v_mul_f32_e32 v41, 0xbfb8aa3b, v25
	v_mul_f32_e32 v42, 0xbfb8aa3b, v33
	v_mul_f32_e32 v43, 0xbfb8aa3b, v19
	v_mul_f32_e32 v44, 0xbfb8aa3b, v27
	v_exp_f32_e32 v45, v45
	v_exp_f32_e32 v34, v34
	v_exp_f32_e32 v35, v35
	v_exp_f32_e32 v40, v40
	v_exp_f32_e32 v41, v41
	v_exp_f32_e32 v42, v42
	v_exp_f32_e32 v43, v43
	v_exp_f32_e32 v44, v44
	v_add_f32_e32 v45, 1.0, v45
	v_add_f32_e32 v34, 1.0, v34
	v_add_f32_e32 v35, 1.0, v35
	v_add_f32_e32 v40, 1.0, v40
	v_add_f32_e32 v41, 1.0, v41
	v_add_f32_e32 v42, 1.0, v42
	v_add_f32_e32 v43, 1.0, v43
	v_add_f32_e32 v44, 1.0, v44
	v_rcp_f32_e32 v45, v45
	v_rcp_f32_e32 v34, v34
	v_rcp_f32_e32 v35, v35
	v_rcp_f32_e32 v40, v40
	v_rcp_f32_e32 v41, v41
	v_rcp_f32_e32 v42, v42
	v_rcp_f32_e32 v43, v43
	v_rcp_f32_e32 v44, v44
	v_mul_f32_e32 v21, v21, v45
	v_mul_f32_e32 v34, v39, v34
	v_mul_f32_e32 v23, v23, v35
	v_mul_f32_e32 v31, v31, v40
	v_mul_f32_e32 v25, v25, v41
	v_mul_f32_e32 v33, v33, v42
	v_mul_f32_e32 v19, v19, v43
	v_mul_f32_e32 v27, v27, v44
	v_mul_f32_e32 v21, v20, v21
	v_mul_f32_e32 v34, v38, v34
	v_mul_f32_e32 v22, v22, v23
	v_mul_f32_e32 v23, v30, v31
	v_mul_f32_e32 v24, v24, v25
	v_mul_f32_e32 v25, v32, v33
	v_mul_f32_e32 v30, v18, v19
	v_mul_f32_e32 v26, v26, v27
	v_cvt_pk_bf16_f32 v18, v34, v22
	v_cvt_pk_bf16_f32 v19, v23, v24
	v_cvt_pk_bf16_f32 v20, v25, v30
	v_cvt_pk_bf16_f32 v21, v26, v21
	global_store_dwordx4 v[28:29], v[18:21], off
	s_nop 0
	v_mov_b32_e32 v34, v14
	v_mov_b32_e32 v35, v10
	v_mov_b32_e32 v10, v15
	v_mov_b32_e32 v14, v16
	v_mov_b32_e32 v15, v12
	v_mov_b32_e32 v12, v17
	v_mov_b32_e32 v16, v6
	v_mov_b32_e32 v17, v2
	v_mov_b32_e32 v2, v7
	v_mov_b32_e32 v6, v8
	v_mov_b32_e32 v7, v4
	v_mov_b32_e32 v4, v9
	s_nop 0
	v_mad_i64_i32 v[18:19], s[0:1], v52, s52, v[146:147]
	v_mov_b32_e32 v8, v233
	v_fmamk_f32 v8, v8, 0x3a800000, v158
	v_rsq_f32_e32 v8, v8
	v_lshl_add_u64 v[18:19], v[18:19], 0, v[122:123]
	v_pk_mul_f32 v[4:5], v[4:5], v[8:9] op_sel_hi:[1,0]
	v_pk_mul_f32 v[20:21], v[34:35], v[8:9] op_sel_hi:[1,0]
	v_pk_mul_f32 v[10:11], v[10:11], v[8:9] op_sel_hi:[1,0]
	v_pk_mul_f32 v[14:15], v[14:15], v[8:9] op_sel_hi:[1,0]
	v_pk_mul_f32 v[12:13], v[12:13], v[8:9] op_sel_hi:[1,0]
	v_pk_mul_f32 v[16:17], v[16:17], v[8:9] op_sel_hi:[1,0]
	v_pk_mul_f32 v[2:3], v[2:3], v[8:9] op_sel_hi:[1,0]
	v_pk_mul_f32 v[6:7], v[6:7], v[8:9] op_sel_hi:[1,0]
	v_mul_f32_e32 v27, 0xbfb8aa3b, v5
	v_mul_f32_e32 v8, 0xbfb8aa3b, v21
	v_mul_f32_e32 v9, 0xbfb8aa3b, v11
	v_mul_f32_e32 v22, 0xbfb8aa3b, v15
	v_mul_f32_e32 v23, 0xbfb8aa3b, v13
	v_mul_f32_e32 v24, 0xbfb8aa3b, v17
	v_mul_f32_e32 v25, 0xbfb8aa3b, v3
	v_mul_f32_e32 v26, 0xbfb8aa3b, v7
	v_exp_f32_e32 v27, v27
	v_exp_f32_e32 v8, v8
	v_exp_f32_e32 v9, v9
	v_exp_f32_e32 v22, v22
	v_exp_f32_e32 v23, v23
	v_exp_f32_e32 v24, v24
	v_exp_f32_e32 v25, v25
	v_exp_f32_e32 v26, v26
	v_add_f32_e32 v27, 1.0, v27
	v_add_f32_e32 v8, 1.0, v8
	v_add_f32_e32 v9, 1.0, v9
	v_add_f32_e32 v22, 1.0, v22
	v_add_f32_e32 v23, 1.0, v23
	v_add_f32_e32 v24, 1.0, v24
	v_add_f32_e32 v25, 1.0, v25
	v_add_f32_e32 v26, 1.0, v26
	v_rcp_f32_e32 v27, v27
	v_rcp_f32_e32 v8, v8
	v_rcp_f32_e32 v9, v9
	v_rcp_f32_e32 v22, v22
	v_rcp_f32_e32 v23, v23
	v_rcp_f32_e32 v24, v24
	v_rcp_f32_e32 v25, v25
	v_rcp_f32_e32 v26, v26
	v_mul_f32_e32 v5, v5, v27
	v_mul_f32_e32 v8, v21, v8
	v_mul_f32_e32 v9, v11, v9
	v_mul_f32_e32 v11, v15, v22
	v_mul_f32_e32 v13, v13, v23
	v_mul_f32_e32 v15, v17, v24
	v_mul_f32_e32 v3, v3, v25
	v_mul_f32_e32 v7, v7, v26
	v_mul_f32_e32 v5, v4, v5
	v_mul_f32_e32 v8, v20, v8
	v_mul_f32_e32 v9, v10, v9
	v_mul_f32_e32 v10, v14, v11
	v_mul_f32_e32 v11, v12, v13
	v_mul_f32_e32 v12, v16, v15
	v_mul_f32_e32 v13, v2, v3
	v_mul_f32_e32 v6, v6, v7
	v_cvt_pk_bf16_f32 v2, v8, v9
	v_cvt_pk_bf16_f32 v3, v10, v11
	v_cvt_pk_bf16_f32 v4, v12, v13
	v_cvt_pk_bf16_f32 v5, v6, v5
	global_store_dwordx4 v[18:19], v[2:5], off
	s_cbranch_vccnz .LBB0_1356
	s_andn2_b64 vcc, exec, s[6:7]
	s_cbranch_vccnz .LBB0_1355
	s_barrier
	s_branch .LBB0_1355
